# v13 = v9 + GQA cross-half max/sum via v_permlane32_swap instead of ds_bpermute
# baseline (speedup 1.0000x reference)
; __device__ __forceinline__ void softmax2_pv(f32x16& sc, float& m, float& l, f32x16& o0, f32x16& o1, const bf16x8 (&vf)[2][2]) {
;     float tm = fmaxf(fmaxf(sc[0], sc[1]), fmaxf(sc[2], sc[3]));
; #pragma unroll
;     for (int i = 4; i < 16; i += 4) tm = fmaxf(tm, fmaxf(fmaxf(sc[i], sc[i + 1]), fmaxf(sc[i + 2], sc[i + 3])));
;     tm = fmaxf(tm, __shfl_xor(tm, 32));
;     const float mn = fmaxf(m, tm);
;     if (__builtin_amdgcn_ballot_w64(mn > m)) {
;         const float alpha = __builtin_amdgcn_exp2f(m - mn);
;         l *= alpha;
; #pragma unroll
;         for (int i = 0; i < 16; ++i) { o0[i] *= alpha; o1[i] *= alpha; }
;         m = mn;
;     }
.LBB0_75:
	s_or_b64 exec, exec, s[24:25]
	v_max_f32_e32 v47, v98, v98
	v_max_f32_e32 v48, v99, v99
	v_max_f32_e32 v47, v48, v47
	v_max_f32_e32 v48, v34, v34
	v_max_f32_e32 v49, v35, v35
	v_max_f32_e32 v48, v49, v48
	v_max_f32_e32 v49, v38, v38
	v_max_f32_e32 v101, v39, v39
	v_max_f32_e32 v49, v101, v49
	v_max3_f32 v49, v37, v36, v49
	v_max3_f32 v47, v47, v48, v49
	v_max_f32_e32 v48, v42, v42
	v_max_f32_e32 v49, v43, v43
	v_max_f32_e32 v48, v49, v48
	v_max_f32_e32 v49, v44, v44
	v_max_f32_e32 v101, v46, v46
	v_max_f32_e32 v49, v101, v49
	v_max3_f32 v48, v41, v40, v48
	v_max3_f32 v49, v100, v45, v49
	v_max3_f32 v47, v47, v48, v49
	v_mov_b32_e32 v48, v47
	s_nop 1
	v_permlane32_swap_b32_e32 v48, v47
	s_waitcnt lgkmcnt(0)
	v_max3_f32 v47, v198, v47, v48
	v_cmp_gt_f32_e32 vcc, v47, v198
	s_cbranch_vccz .LBB0_117
	v_sub_f32_e32 v48, v198, v47
	v_exp_f32_e32 v48, v48
	s_nop 0
	v_mul_f32_e32 v0, v0, v48
	v_pk_mul_f32 v[32:33], v[32:33], v[48:49] op_sel_hi:[1,0]
	v_pk_mul_f32 v[30:31], v[30:31], v[48:49] op_sel_hi:[1,0]
	v_pk_mul_f32 v[28:29], v[28:29], v[48:49] op_sel_hi:[1,0]
	v_pk_mul_f32 v[26:27], v[26:27], v[48:49] op_sel_hi:[1,0]
	v_pk_mul_f32 v[24:25], v[24:25], v[48:49] op_sel_hi:[1,0]
	v_pk_mul_f32 v[22:23], v[22:23], v[48:49] op_sel_hi:[1,0]
	v_pk_mul_f32 v[20:21], v[20:21], v[48:49] op_sel_hi:[1,0]
	v_pk_mul_f32 v[18:19], v[18:19], v[48:49] op_sel_hi:[1,0]
	v_pk_mul_f32 v[16:17], v[16:17], v[48:49] op_sel_hi:[1,0]
	v_pk_mul_f32 v[14:15], v[14:15], v[48:49] op_sel_hi:[1,0]
	v_pk_mul_f32 v[12:13], v[12:13], v[48:49] op_sel_hi:[1,0]
	v_pk_mul_f32 v[10:11], v[10:11], v[48:49] op_sel_hi:[1,0]
	v_pk_mul_f32 v[8:9], v[8:9], v[48:49] op_sel_hi:[1,0]
	v_pk_mul_f32 v[6:7], v[6:7], v[48:49] op_sel_hi:[1,0]
	v_pk_mul_f32 v[4:5], v[4:5], v[48:49] op_sel_hi:[1,0]
	v_pk_mul_f32 v[2:3], v[2:3], v[48:49] op_sel_hi:[1,0]

; __device__ __forceinline__ unsigned pk2(float lo, float hi) { return f2bf(lo) | (f2bf(hi) << 16); }
; __device__ __forceinline__ void attn_store(bf16_t* op  , const f32x16& o0, const f32x16& o1, float inv) {
; #pragma unroll
;     for (int a = 0; a < 4; ++a) {
;         u32x2 w; w.x = pk2(o0[4 * a] * inv, o0[4 * a + 1] * inv); w.y = pk2(o0[4 * a + 2] * inv, o0[4 * a + 3] * inv); *(u32x2*)(op + 8 * a) = w;
;         u32x2 x; x.x = pk2(o1[4 * a] * inv, o1[4 * a + 1] * inv); x.y = pk2(o1[4 * a + 2] * inv, o1[4 * a + 3] * inv); *(u32x2*)(op + 32 + 8 * a) = x;
;     }
; }
; __device__ __forceinline__ void gqa_phase(const PP P, LAS unsigned char* lds, int tid, int cb, int G) {
;     ...
;             l += __shfl_xor(l, 32);
;             attn_store(MIX + (size_t)(m0 + qoff + r32) * D + head * 64 + 4 * hi, o0, o1, 1.0f / l);
.LBB0_78:
	v_mov_b32_e32 v37, v0
	s_nop 1
	v_permlane32_swap_b32_e32 v37, v0
	s_nop 3
	v_mov_b32_e32 v36, v18
	v_lshlrev_b64 v[34:35], 11, v[146:147]
	v_lshl_add_u64 v[34:35], v[144:145], 0, v[34:35]
	s_mov_b64 s[24:25], 0
	s_waitcnt lgkmcnt(0)
	v_add_f32_e32 v0, v0, v37
	v_div_scale_f32 v18, s[18:19], v0, v0, 1.0
	v_rcp_f32_e32 v37, v18
	v_div_scale_f32 v38, vcc, 1.0, v0, 1.0
	s_mov_b32 s18, 32
	v_fma_f32 v39, -v18, v37, 1.0
	v_fmac_f32_e32 v37, v39, v37
	v_mul_f32_e32 v39, v38, v37
	v_fma_f32 v40, -v18, v39, v38
	v_fmac_f32_e32 v39, v40, v37
	v_fma_f32 v18, -v18, v39, v38
	v_div_fmas_f32 v18, v18, v37, v39
	v_div_fixup_f32 v0, v18, v0, 1.0
	v_mov_b32_e32 v37, v20
	v_pk_mul_f32 v[36:37], v[36:37], v[0:1] op_sel_hi:[1,0]
	v_mov_b32_e32 v20, v19
	v_pk_mul_f32 v[18:19], v[20:21], v[0:1] op_sel_hi:[1,0]
	v_and_b32_sdwa v20, v37, v243 dst_sel:DWORD dst_unused:UNUSED_PAD src0_sel:WORD_1 src1_sel:DWORD
	v_and_b32_sdwa v21, v36, v243 dst_sel:DWORD dst_unused:UNUSED_PAD src0_sel:WORD_1 src1_sel:DWORD
	v_add3_u32 v21, v36, v21, s14
	v_add3_u32 v20, v37, v20, s14
	v_and_b32_sdwa v36, v19, v243 dst_sel:DWORD dst_unused:UNUSED_PAD src0_sel:WORD_1 src1_sel:DWORD
	v_and_b32_sdwa v37, v18, v243 dst_sel:DWORD dst_unused:UNUSED_PAD src0_sel:WORD_1 src1_sel:DWORD
	v_add3_u32 v19, v19, v36, s14
	v_add3_u32 v18, v18, v37, s14
	v_and_b32_e32 v19, 0xffff0000, v19
	v_and_b32_e32 v18, 0xffff0000, v18
	v_or_b32_sdwa v19, v19, v20 dst_sel:DWORD dst_unused:UNUSED_PAD src0_sel:DWORD src1_sel:WORD_1
	v_or_b32_sdwa v18, v18, v21 dst_sel:DWORD dst_unused:UNUSED_PAD src0_sel:DWORD src1_sel:WORD_1
	global_store_dwordx2 v[34:35], v[18:19], off
	v_mov_b32_e32 v18, v2
	v_mov_b32_e32 v19, v4
	v_pk_mul_f32 v[18:19], v[18:19], v[0:1] op_sel_hi:[1,0]
	v_mov_b32_e32 v4, v3
	v_pk_mul_f32 v[2:3], v[4:5], v[0:1] op_sel_hi:[1,0]
	v_and_b32_sdwa v4, v19, v243 dst_sel:DWORD dst_unused:UNUSED_PAD src0_sel:WORD_1 src1_sel:DWORD
	v_and_b32_sdwa v5, v18, v243 dst_sel:DWORD dst_unused:UNUSED_PAD src0_sel:WORD_1 src1_sel:DWORD
	v_add3_u32 v5, v18, v5, s14
	v_add3_u32 v4, v19, v4, s14
	v_and_b32_sdwa v18, v3, v243 dst_sel:DWORD dst_unused:UNUSED_PAD src0_sel:WORD_1 src1_sel:DWORD
	v_and_b32_sdwa v19, v2, v243 dst_sel:DWORD dst_unused:UNUSED_PAD src0_sel:WORD_1 src1_sel:DWORD
	v_add3_u32 v3, v3, v18, s14
	v_add3_u32 v2, v2, v19, s14
	v_and_b32_e32 v3, 0xffff0000, v3
	v_and_b32_e32 v2, 0xffff0000, v2
	v_or_b32_sdwa v3, v3, v4 dst_sel:DWORD dst_unused:UNUSED_PAD src0_sel:DWORD src1_sel:WORD_1
	v_or_b32_sdwa v2, v2, v5 dst_sel:DWORD dst_unused:UNUSED_PAD src0_sel:DWORD src1_sel:WORD_1
	global_store_dwordx2 v[34:35], v[2:3], off offset:64
	v_mov_b32_e32 v2, v22
	v_mov_b32_e32 v3, v24
	v_pk_mul_f32 v[2:3], v[2:3], v[0:1] op_sel_hi:[1,0]
	v_mov_b32_e32 v24, v23
	v_pk_mul_f32 v[4:5], v[24:25], v[0:1] op_sel_hi:[1,0]
	v_and_b32_sdwa v18, v3, v243 dst_sel:DWORD dst_unused:UNUSED_PAD src0_sel:WORD_1 src1_sel:DWORD
	v_and_b32_sdwa v19, v2, v243 dst_sel:DWORD dst_unused:UNUSED_PAD src0_sel:WORD_1 src1_sel:DWORD
	v_add3_u32 v2, v2, v19, s14
	v_add3_u32 v3, v3, v18, s14
	v_and_b32_sdwa v18, v5, v243 dst_sel:DWORD dst_unused:UNUSED_PAD src0_sel:WORD_1 src1_sel:DWORD
	v_and_b32_sdwa v19, v4, v243 dst_sel:DWORD dst_unused:UNUSED_PAD src0_sel:WORD_1 src1_sel:DWORD
	v_add3_u32 v5, v5, v18, s14
	v_add3_u32 v4, v4, v19, s14
	v_and_b32_e32 v5, 0xffff0000, v5
	v_and_b32_e32 v4, 0xffff0000, v4
	v_or_b32_sdwa v3, v5, v3 dst_sel:DWORD dst_unused:UNUSED_PAD src0_sel:DWORD src1_sel:WORD_1
	v_or_b32_sdwa v2, v4, v2 dst_sel:DWORD dst_unused:UNUSED_PAD src0_sel:DWORD src1_sel:WORD_1
	global_store_dwordx2 v[34:35], v[2:3], off offset:16
	v_mov_b32_e32 v2, v6
	v_mov_b32_e32 v3, v8
	v_pk_mul_f32 v[2:3], v[2:3], v[0:1] op_sel_hi:[1,0]
	v_mov_b32_e32 v8, v7
	v_pk_mul_f32 v[4:5], v[8:9], v[0:1] op_sel_hi:[1,0]
	v_and_b32_sdwa v6, v3, v243 dst_sel:DWORD dst_unused:UNUSED_PAD src0_sel:WORD_1 src1_sel:DWORD
	v_and_b32_sdwa v7, v2, v243 dst_sel:DWORD dst_unused:UNUSED_PAD src0_sel:WORD_1 src1_sel:DWORD
	v_add3_u32 v2, v2, v7, s14
	v_add3_u32 v3, v3, v6, s14
	v_and_b32_sdwa v6, v5, v243 dst_sel:DWORD dst_unused:UNUSED_PAD src0_sel:WORD_1 src1_sel:DWORD
	v_and_b32_sdwa v7, v4, v243 dst_sel:DWORD dst_unused:UNUSED_PAD src0_sel:WORD_1 src1_sel:DWORD
	v_add3_u32 v5, v5, v6, s14
	v_add3_u32 v4, v4, v7, s14
; __device__ __forceinline__ unsigned pk2(float lo, float hi) { return f2bf(lo) | (f2bf(hi) << 16); }
; __device__ __forceinline__ void attn_store(bf16_t* op  , const f32x16& o0, const f32x16& o1, float inv) {
; #pragma unroll
;     for (int a = 0; a < 4; ++a) {
;         u32x2 w; w.x = pk2(o0[4 * a] * inv, o0[4 * a + 1] * inv); w.y = pk2(o0[4 * a + 2] * inv, o0[4 * a + 3] * inv); *(u32x2*)(op + 8 * a) = w;
;         u32x2 x; x.x = pk2(o1[4 * a] * inv, o1[4 * a + 1] * inv); x.y = pk2(o1[4 * a + 2] * inv, o1[4 * a + 3] * inv); *(u32x2*)(op + 32 + 8 * a) = x;
;     }
; }
	v_and_b32_e32 v5, 0xffff0000, v5
	v_and_b32_e32 v4, 0xffff0000, v4
	v_or_b32_sdwa v3, v5, v3 dst_sel:DWORD dst_unused:UNUSED_PAD src0_sel:DWORD src1_sel:WORD_1
	v_or_b32_sdwa v2, v4, v2 dst_sel:DWORD dst_unused:UNUSED_PAD src0_sel:DWORD src1_sel:WORD_1
	global_store_dwordx2 v[34:35], v[2:3], off offset:80
	v_mov_b32_e32 v2, v26
	v_mov_b32_e32 v3, v28
	v_pk_mul_f32 v[2:3], v[2:3], v[0:1] op_sel_hi:[1,0]
	v_mov_b32_e32 v28, v27
	v_pk_mul_f32 v[4:5], v[28:29], v[0:1] op_sel_hi:[1,0]
	v_and_b32_sdwa v6, v3, v243 dst_sel:DWORD dst_unused:UNUSED_PAD src0_sel:WORD_1 src1_sel:DWORD
	v_and_b32_sdwa v7, v2, v243 dst_sel:DWORD dst_unused:UNUSED_PAD src0_sel:WORD_1 src1_sel:DWORD
	v_add3_u32 v2, v2, v7, s14
	v_add3_u32 v3, v3, v6, s14
	v_and_b32_sdwa v6, v5, v243 dst_sel:DWORD dst_unused:UNUSED_PAD src0_sel:WORD_1 src1_sel:DWORD
	v_and_b32_sdwa v7, v4, v243 dst_sel:DWORD dst_unused:UNUSED_PAD src0_sel:WORD_1 src1_sel:DWORD
	v_add3_u32 v5, v5, v6, s14
	v_add3_u32 v4, v4, v7, s14
	v_and_b32_e32 v5, 0xffff0000, v5
	v_and_b32_e32 v4, 0xffff0000, v4
	v_or_b32_sdwa v3, v5, v3 dst_sel:DWORD dst_unused:UNUSED_PAD src0_sel:DWORD src1_sel:WORD_1
	v_or_b32_sdwa v2, v4, v2 dst_sel:DWORD dst_unused:UNUSED_PAD src0_sel:DWORD src1_sel:WORD_1
	global_store_dwordx2 v[34:35], v[2:3], off offset:32
	v_mov_b32_e32 v2, v10
	v_mov_b32_e32 v3, v12
	v_pk_mul_f32 v[2:3], v[2:3], v[0:1] op_sel_hi:[1,0]
	v_mov_b32_e32 v12, v11
	v_pk_mul_f32 v[4:5], v[12:13], v[0:1] op_sel_hi:[1,0]
	v_and_b32_sdwa v6, v3, v243 dst_sel:DWORD dst_unused:UNUSED_PAD src0_sel:WORD_1 src1_sel:DWORD
	v_and_b32_sdwa v7, v2, v243 dst_sel:DWORD dst_unused:UNUSED_PAD src0_sel:WORD_1 src1_sel:DWORD
	v_add3_u32 v2, v2, v7, s14
	v_add3_u32 v3, v3, v6, s14
	v_and_b32_sdwa v6, v5, v243 dst_sel:DWORD dst_unused:UNUSED_PAD src0_sel:WORD_1 src1_sel:DWORD
	v_and_b32_sdwa v7, v4, v243 dst_sel:DWORD dst_unused:UNUSED_PAD src0_sel:WORD_1 src1_sel:DWORD
	v_add3_u32 v5, v5, v6, s14
	v_add3_u32 v4, v4, v7, s14
	v_and_b32_e32 v5, 0xffff0000, v5
	v_and_b32_e32 v4, 0xffff0000, v4
	v_or_b32_sdwa v3, v5, v3 dst_sel:DWORD dst_unused:UNUSED_PAD src0_sel:DWORD src1_sel:WORD_1
	v_or_b32_sdwa v2, v4, v2 dst_sel:DWORD dst_unused:UNUSED_PAD src0_sel:DWORD src1_sel:WORD_1
	global_store_dwordx2 v[34:35], v[2:3], off offset:96
	v_mov_b32_e32 v2, v30
	v_mov_b32_e32 v3, v32
	v_pk_mul_f32 v[2:3], v[2:3], v[0:1] op_sel_hi:[1,0]
	v_mov_b32_e32 v32, v31
	v_pk_mul_f32 v[4:5], v[32:33], v[0:1] op_sel_hi:[1,0]
	v_and_b32_sdwa v6, v3, v243 dst_sel:DWORD dst_unused:UNUSED_PAD src0_sel:WORD_1 src1_sel:DWORD
	v_and_b32_sdwa v7, v2, v243 dst_sel:DWORD dst_unused:UNUSED_PAD src0_sel:WORD_1 src1_sel:DWORD
	v_add3_u32 v2, v2, v7, s14
	v_add3_u32 v3, v3, v6, s14
	v_and_b32_sdwa v6, v5, v243 dst_sel:DWORD dst_unused:UNUSED_PAD src0_sel:WORD_1 src1_sel:DWORD
	v_and_b32_sdwa v7, v4, v243 dst_sel:DWORD dst_unused:UNUSED_PAD src0_sel:WORD_1 src1_sel:DWORD
	v_add3_u32 v5, v5, v6, s14
	v_add3_u32 v4, v4, v7, s14
	v_and_b32_e32 v5, 0xffff0000, v5
	v_and_b32_e32 v4, 0xffff0000, v4
	v_or_b32_sdwa v3, v5, v3 dst_sel:DWORD dst_unused:UNUSED_PAD src0_sel:DWORD src1_sel:WORD_1
	v_or_b32_sdwa v2, v4, v2 dst_sel:DWORD dst_unused:UNUSED_PAD src0_sel:DWORD src1_sel:WORD_1
	global_store_dwordx2 v[34:35], v[2:3], off offset:48
	v_mov_b32_e32 v2, v14
	v_mov_b32_e32 v3, v16
	v_pk_mul_f32 v[2:3], v[2:3], v[0:1] op_sel_hi:[1,0]
	v_mov_b32_e32 v16, v15
	v_pk_mul_f32 v[4:5], v[16:17], v[0:1] op_sel_hi:[1,0]
	v_and_b32_sdwa v0, v3, v243 dst_sel:DWORD dst_unused:UNUSED_PAD src0_sel:WORD_1 src1_sel:DWORD
	v_and_b32_sdwa v6, v2, v243 dst_sel:DWORD dst_unused:UNUSED_PAD src0_sel:WORD_1 src1_sel:DWORD
	v_add3_u32 v2, v2, v6, s14
	v_add3_u32 v0, v3, v0, s14
	v_and_b32_sdwa v3, v5, v243 dst_sel:DWORD dst_unused:UNUSED_PAD src0_sel:WORD_1 src1_sel:DWORD
	v_and_b32_sdwa v6, v4, v243 dst_sel:DWORD dst_unused:UNUSED_PAD src0_sel:WORD_1 src1_sel:DWORD
	v_add3_u32 v3, v5, v3, s14
	v_add3_u32 v4, v4, v6, s14
	v_and_b32_e32 v3, 0xffff0000, v3
	v_and_b32_e32 v4, 0xffff0000, v4
	v_or_b32_sdwa v3, v3, v0 dst_sel:DWORD dst_unused:UNUSED_PAD src0_sel:DWORD src1_sel:WORD_1
	v_or_b32_sdwa v2, v4, v2 dst_sel:DWORD dst_unused:UNUSED_PAD src0_sel:DWORD src1_sel:WORD_1
	s_and_b64 vcc, exec, s[12:13]
	global_store_dwordx2 v[34:35], v[2:3], off offset:112
	s_cbranch_vccnz .LBB0_45

; #define MFMA32(a, b, c) __builtin_amdgcn_mfma_f32_32x32x16_bf16((a), (b), (c), 0, 0, 0)
; __device__ __forceinline__ unsigned cvtpk_s(float lo, float hi) { f32x2_t v = {lo, hi}; bf16x2_t r = __builtin_convertvector(v, bf16x2_t); return __builtin_bit_cast(unsigned, r); }
; __device__ __forceinline__ void softmax2_pv(f32x16& sc, float& m, float& l, f32x16& o0, f32x16& o1, const bf16x8 (&vf)[2][2]) {
;     float tm = fmaxf(fmaxf(sc[0], sc[1]), fmaxf(sc[2], sc[3]));
; #pragma unroll
;     for (int i = 4; i < 16; i += 4) tm = fmaxf(tm, fmaxf(fmaxf(sc[i], sc[i + 1]), fmaxf(sc[i + 2], sc[i + 3])));
;     tm = fmaxf(tm, __shfl_xor(tm, 32));
;     const float mn = fmaxf(m, tm);
;     if (__builtin_amdgcn_ballot_w64(mn > m)) {
;         const float alpha = __builtin_amdgcn_exp2f(m - mn);
;         l *= alpha;
; #pragma unroll
;         for (int i = 0; i < 16; ++i) { o0[i] *= alpha; o1[i] *= alpha; }
;         m = mn;
;     }
;     float ps = 0.f;
; #pragma unroll
;     for (int i = 0; i < 16; ++i) { const float pv = __builtin_amdgcn_exp2f(sc[i] - m); sc[i] = pv; ps += pv; }
;     l += ps;
;     u32x4 w0, w1;
;     w0.x = cvtpk_s(sc[0], sc[1]); w0.y = cvtpk_s(sc[2], sc[3]); w0.z = cvtpk_s(sc[4], sc[5]); w0.w = cvtpk_s(sc[6], sc[7]);
;     w1.x = cvtpk_s(sc[8], sc[9]); w1.y = cvtpk_s(sc[10], sc[11]); w1.z = cvtpk_s(sc[12], sc[13]); w1.w = cvtpk_s(sc[14], sc[15]);
;     const bf16x8 pf0 = __builtin_bit_cast(bf16x8, w0), pf1 = __builtin_bit_cast(bf16x8, w1);
;     o0 = MFMA32(vf[0][0], pf0, o0); o0 = MFMA32(vf[0][1], pf1, o0);
;     o1 = MFMA32(vf[1][0], pf0, o1); o1 = MFMA32(vf[1][1], pf1, o1);
.LBB0_112:
	s_or_b64 exec, exec, s[12:13]
	v_max_f32_e32 v2, v0, v0
	v_max_f32_e32 v3, v18, v18
	v_max_f32_e32 v2, v3, v2
	v_max_f32_e32 v3, v19, v19
	v_max_f32_e32 v4, v20, v20
	v_max_f32_e32 v3, v4, v3
	v_max_f32_e32 v4, v23, v23
	v_max_f32_e32 v5, v24, v24
	v_max_f32_e32 v4, v5, v4
	v_max3_f32 v4, v22, v21, v4
	v_max3_f32 v2, v2, v3, v4
	v_max_f32_e32 v3, v27, v27
	v_max_f32_e32 v4, v28, v28
	v_max_f32_e32 v3, v4, v3
	v_max_f32_e32 v4, v114, v114
	v_max_f32_e32 v5, v31, v31
	v_max_f32_e32 v4, v5, v4
	v_max3_f32 v3, v26, v25, v3
	v_max3_f32 v4, v30, v29, v4
	v_max3_f32 v2, v2, v3, v4
	v_mov_b32_e32 v3, v2
	s_nop 1
	v_permlane32_swap_b32_e32 v3, v2
	s_waitcnt lgkmcnt(0)
	v_max3_f32 v2, v196, v2, v3
	v_cmp_gt_f32_e32 vcc, v2, v196
	s_cmp_eq_u64 vcc, 0
	s_cselect_b64 vcc, -1, 0
	v_cndmask_b32_e32 v198, v2, v196, vcc
	v_sub_f32_e32 v19, v19, v198
	v_exp_f32_e32 v121, v19
	v_sub_f32_e32 v19, v22, v198
	v_exp_f32_e32 v147, v19
	v_sub_f32_e32 v19, v21, v198
	v_sub_f32_e32 v3, v196, v2
	v_exp_f32_e32 v148, v19
	v_sub_f32_e32 v19, v24, v198
	v_exp_f32_e32 v3, v3
	v_sub_f32_e32 v17, v18, v198
	v_exp_f32_e32 v149, v19
	v_sub_f32_e32 v19, v23, v198
	v_exp_f32_e32 v18, v17
	v_sub_f32_e32 v0, v0, v198
	v_sub_f32_e32 v17, v20, v198
	v_exp_f32_e32 v150, v19
	v_sub_f32_e32 v19, v26, v198
	v_exp_f32_e32 v0, v0
	v_exp_f32_e32 v20, v17
	v_exp_f32_e32 v151, v19
	v_sub_f32_e32 v19, v25, v198
	v_exp_f32_e32 v152, v19
	v_sub_f32_e32 v19, v28, v198
	v_mul_f32_e32 v4, 0, v3
	v_exp_f32_e32 v153, v19
	v_sub_f32_e32 v19, v27, v198
	v_cndmask_b32_e64 v2, v4, 0, vcc
	v_add_f32_e32 v32, 0, v18
	v_exp_f32_e32 v154, v19
	v_sub_f32_e32 v19, v30, v198
	v_cndmask_b32_e64 v115, v3, 1.0, vcc
	v_mov_b32_e32 v3, v2
	v_mov_b32_e32 v4, v2
	v_mov_b32_e32 v5, v2
	v_mov_b32_e32 v6, v2
	v_mov_b32_e32 v7, v2
	v_mov_b32_e32 v8, v2
	v_mov_b32_e32 v9, v2
	v_mov_b32_e32 v10, v2
	v_mov_b32_e32 v11, v2
	v_mov_b32_e32 v12, v2
	v_mov_b32_e32 v13, v2
	v_mov_b32_e32 v14, v2
	v_mov_b32_e32 v15, v2
	v_mov_b32_e32 v16, v2
	v_mov_b32_e32 v17, v2
	v_add_f32_e32 v32, v0, v32
	v_exp_f32_e32 v155, v19
	v_sub_f32_e32 v19, v29, v198
	v_cvt_pk_bf16_f32 v116, v18, v0
	v_cvt_pk_bf16_f32 v117, v20, v121
	v_cvt_pk_bf16_f32 v118, v147, v148
	v_cvt_pk_bf16_f32 v119, v149, v150
	v_add_f32_e32 v120, v20, v32
	v_exp_f32_e32 v156, v19
	v_sub_f32_e32 v157, v31, v198
	v_mfma_f32_32x32x16_bf16 v[18:33], v[46:49], v[116:119], v[2:17]
	v_sub_f32_e32 v46, v114, v198
	v_exp_f32_e32 v0, v157
	v_exp_f32_e32 v114, v46
	v_cvt_pk_bf16_f32 v46, v151, v152
	v_cvt_pk_bf16_f32 v47, v153, v154
	v_cvt_pk_bf16_f32 v48, v155, v156
	v_cvt_pk_bf16_f32 v49, v0, v114
	v_mfma_f32_32x32x16_bf16 v[2:17], v[38:41], v[116:119], v[2:17]
	s_nop 0
	v_mfma_f32_32x32x16_bf16 v[18:33], v[42:45], v[46:49], v[18:33]
	v_add_f32_e32 v42, v121, v120
	v_add_f32_e32 v42, v147, v42
	v_add_f32_e32 v42, v148, v42
	v_add_f32_e32 v42, v149, v42
	v_add_f32_e32 v42, v150, v42
	v_add_f32_e32 v42, v151, v42
	v_add_f32_e32 v42, v152, v42
	v_mfma_f32_32x32x16_bf16 v[2:17], v[34:37], v[46:49], v[2:17]
	v_add_f32_e32 v38, v153, v42
	v_add_f32_e32 v38, v154, v38
	v_add_f32_e32 v38, v155, v38
	v_add_f32_e32 v38, v156, v38
	v_add_f32_e32 v0, v0, v38
	v_add_f32_e32 v0, v114, v0
	v_fmac_f32_e32 v0, v165, v115
	s_branch .LBB0_114

; #define LAS __attribute__((address_space(3)))
; #define MFMA32(a, b, c) __builtin_amdgcn_mfma_f32_32x32x16_bf16((a), (b), (c), 0, 0, 0)
; __device__ __forceinline__ void gqa_phase(const PP P, LAS unsigned char* lds, int tid, int cb, int G) {
;     ...
;             for (int t = 0; t < 9; ++t) {
;                 const int kr0 = qoff + 32 * t, tok0 = m0 - 128 + kr0;
;                 if (tok0 < row0 || tok0 >= row0 + L) continue;
;                 bf16x8 kf[4];
; #pragma unroll
;                 for (int ds = 0; ds < 4; ++ds) kf[ds] = *(const LAS bf16x8*)(lds + GQ_K + (kr0 + r32) * GK_PITCH + (16 * ds + 8 * hi) * 2);
;                 bf16x8 vf[2][2];
; #pragma unroll
;                 for (int dh = 0; dh < 2; ++dh)
; #pragma unroll
;                     for (int s = 0; s < 2; ++s) { const LAS s16x4* vp = (const LAS s16x4*)(lds + GQ_V + (dh * 32 + r32) * GV_PITCH + (kr0 + 16 * s + 4 * hi) * 2);
;                         const s16x4 a = vp[0], c2 = vp[2]; vf[dh][s] = (bf16x8){a[0], a[1], a[2], a[3], c2[0], c2[1], c2[2], c2[3]}; }
;                 f32x16 sc = {};
; #pragma unroll
;                 for (int ds = 0; ds < 4; ++ds) sc = MFMA32(kf[ds], qr[ds], sc);
;                 const int ib = 32 * t - r32 + 4 * hi;
;                 if (t == 0 || t == 8) {
; #pragma unroll
;                     for (int i = 0; i < 16; ++i) { const int ix = ib + (i & 3) + 8 * (i >> 2); const bool valid = ix >= 0 && ix <= 256; const float bb = tbl[valid ? ix : 0];
;                         sc[i] = valid ? sc[i] * (0.125f * LOG2E) + bb : NEGBIG; }
;                 } else {
; #pragma unroll
;                     for (int i = 0; i < 16; ++i) sc[i] = sc[i] * (0.125f * LOG2E) + tbl[ib + (i & 3) + 8 * (i >> 2)];
;                 }
;                 softmax2_pv(sc, m, l, o0, o1, vf);
.LBB0_114:
	s_add_i32 s18, s22, 32
	s_xor_b64 s[12:13], s[24:25], -1
	s_add_i32 s19, s35, s18
	s_cmp_ge_i32 s19, s3
	s_cselect_b64 s[24:25], -1, 0
	s_cmp_lt_i32 s19, s20
	s_cselect_b64 vcc, -1, 0
	s_and_b64 s[24:25], s[24:25], vcc
	v_ashrrev_i32_e32 v147, 31, v146
	s_andn2_b64 vcc, exec, s[24:25]
	s_cbranch_vccnz .LBB0_120
	v_or_b32_e32 v34, s18, v164
	v_mad_u32_u24 v118, v34, s26, v166
	ds_read_b128 v[34:37], v118
	ds_read_b128 v[114:117], v118 offset:32
	s_lshl_b32 s18, s18, 1
	s_waitcnt lgkmcnt(1)
	v_mfma_f32_32x32x16_bf16 v[34:49], v[34:37], v[110:113], 0
	s_waitcnt lgkmcnt(0)
	v_mfma_f32_32x32x16_bf16 v[34:49], v[114:117], v[106:109], v[34:49]
	ds_read_b128 v[114:117], v118 offset:64
	ds_read2_b32 v[162:163], v181 offset0:32 offset1:33
	ds_read2_b32 v[160:161], v181 offset0:34 offset1:35
	ds_read2_b32 v[154:155], v181 offset0:40 offset1:41
	ds_read2_b32 v[150:151], v181 offset0:42 offset1:43
	ds_read_b128 v[206:209], v118 offset:96
	ds_read2_b32 v[156:157], v181 offset0:48 offset1:49
	ds_read2_b32 v[158:159], v181 offset0:50 offset1:51
	ds_read2_b32 v[152:153], v181 offset0:56 offset1:57
	ds_read2_b32 v[148:149], v181 offset0:58 offset1:59
	s_waitcnt lgkmcnt(9)
	v_mfma_f32_32x32x16_bf16 v[34:49], v[114:117], v[102:105], v[34:49]
	v_add_u32_e32 v114, s18, v179
	v_add_u32_e32 v114, 0xd800, v114
	ds_read2_b64 v[118:121], v114 offset1:2
	ds_read2_b64 v[114:117], v114 offset0:4 offset1:6
	s_waitcnt lgkmcnt(6)
	v_mfma_f32_32x32x16_bf16 v[34:49], v[206:209], v[98:101], v[34:49]
	s_nop 11
	v_fmamk_f32 v199, v36, 0x3e38aa3b, v160
	v_fmamk_f32 v160, v40, 0x3e38aa3b, v150
	v_fmac_f32_e32 v151, 0x3e38aa3b, v41
	v_fmamk_f32 v200, v34, 0x3e38aa3b, v162
	v_fmac_f32_e32 v163, 0x3e38aa3b, v35
	v_fmac_f32_e32 v161, 0x3e38aa3b, v37
	v_fmamk_f32 v162, v38, 0x3e38aa3b, v154
	v_fmac_f32_e32 v155, 0x3e38aa3b, v39
	s_waitcnt lgkmcnt(5)
	v_fmac_f32_e32 v157, 0x3e38aa3b, v43
	s_waitcnt lgkmcnt(4)
	v_fmamk_f32 v150, v44, 0x3e38aa3b, v158
	v_fmac_f32_e32 v159, 0x3e38aa3b, v45
	s_waitcnt lgkmcnt(2)
	v_fmamk_f32 v43, v48, 0x3e38aa3b, v148
	v_fmac_f32_e32 v149, 0x3e38aa3b, v49
	v_max_f32_e32 v36, v160, v151
	v_fmamk_f32 v154, v42, 0x3e38aa3b, v156
	v_fmamk_f32 v44, v46, 0x3e38aa3b, v152
	v_fmac_f32_e32 v153, 0x3e38aa3b, v47
	v_max_f32_e32 v34, v200, v163
	v_max_f32_e32 v35, v199, v161
	v_max_f32_e32 v37, v150, v159
	v_max_f32_e32 v38, v43, v149
	v_max3_f32 v36, v162, v155, v36
	v_max3_f32 v37, v154, v157, v37
	v_max3_f32 v34, v34, v35, v36
	v_max3_f32 v35, v44, v153, v38
	v_max3_f32 v42, v34, v37, v35
	v_mov_b32_e32 v45, v42
	s_nop 1
	v_permlane32_swap_b32_e32 v45, v42
	v_add_u32_e32 v34, s18, v180
	v_add_u32_e32 v34, 0x6000, v34
	ds_read2_b64 v[38:41], v34 offset0:32 offset1:34
	ds_read2_b64 v[34:37], v34 offset0:36 offset1:38
	s_waitcnt lgkmcnt(2)
	v_max3_f32 v42, v198, v42, v45
	v_cmp_gt_f32_e32 vcc, v42, v198
	s_cbranch_vccz .LBB0_118
	v_sub_f32_e32 v45, v198, v42
	v_exp_f32_e32 v46, v45
	v_mov_b32_e32 v198, v42
	v_mul_f32_e32 v0, v0, v46
	v_pk_mul_f32 v[32:33], v[32:33], v[46:47] op_sel_hi:[1,0]
	v_pk_mul_f32 v[30:31], v[30:31], v[46:47] op_sel_hi:[1,0]
	v_pk_mul_f32 v[28:29], v[28:29], v[46:47] op_sel_hi:[1,0]
	v_pk_mul_f32 v[26:27], v[26:27], v[46:47] op_sel_hi:[1,0]
	v_pk_mul_f32 v[24:25], v[24:25], v[46:47] op_sel_hi:[1,0]
	v_pk_mul_f32 v[22:23], v[22:23], v[46:47] op_sel_hi:[1,0]
	v_pk_mul_f32 v[20:21], v[20:21], v[46:47] op_sel_hi:[1,0]
	v_pk_mul_f32 v[18:19], v[18:19], v[46:47] op_sel_hi:[1,0]
	v_pk_mul_f32 v[16:17], v[16:17], v[46:47] op_sel_hi:[1,0]
	v_pk_mul_f32 v[14:15], v[14:15], v[46:47] op_sel_hi:[1,0]
	v_pk_mul_f32 v[12:13], v[12:13], v[46:47] op_sel_hi:[1,0]
	v_pk_mul_f32 v[10:11], v[10:11], v[46:47] op_sel_hi:[1,0]
	v_pk_mul_f32 v[8:9], v[8:9], v[46:47] op_sel_hi:[1,0]
	v_pk_mul_f32 v[6:7], v[6:7], v[46:47] op_sel_hi:[1,0]
	v_pk_mul_f32 v[4:5], v[4:5], v[46:47] op_sel_hi:[1,0]
	v_pk_mul_f32 v[2:3], v[2:3], v[46:47] op_sel_hi:[1,0]
	s_branch .LBB0_119

; #define LAS __attribute__((address_space(3)))
; #define MFMA32(a, b, c) __builtin_amdgcn_mfma_f32_32x32x16_bf16((a), (b), (c), 0, 0, 0)
; __device__ __forceinline__ void gqa_phase(const PP P, LAS unsigned char* lds, int tid, int cb, int G) {
;     ...
;             for (int t = 0; t < 9; ++t) {
;                 const int kr0 = qoff + 32 * t, tok0 = m0 - 128 + kr0;
;                 if (tok0 < row0 || tok0 >= row0 + L) continue;
;                 bf16x8 kf[4];
; #pragma unroll
;                 for (int ds = 0; ds < 4; ++ds) kf[ds] = *(const LAS bf16x8*)(lds + GQ_K + (kr0 + r32) * GK_PITCH + (16 * ds + 8 * hi) * 2);
;                 bf16x8 vf[2][2];
; #pragma unroll
;                 for (int dh = 0; dh < 2; ++dh)
; #pragma unroll
;                     for (int s = 0; s < 2; ++s) { const LAS s16x4* vp = (const LAS s16x4*)(lds + GQ_V + (dh * 32 + r32) * GV_PITCH + (kr0 + 16 * s + 4 * hi) * 2);
;                         const s16x4 a = vp[0], c2 = vp[2]; vf[dh][s] = (bf16x8){a[0], a[1], a[2], a[3], c2[0], c2[1], c2[2], c2[3]}; }
;                 f32x16 sc = {};
; #pragma unroll
;                 for (int ds = 0; ds < 4; ++ds) sc = MFMA32(kf[ds], qr[ds], sc);
;                 const int ib = 32 * t - r32 + 4 * hi;
;                 if (t == 0 || t == 8) {
; #pragma unroll
;                     for (int i = 0; i < 16; ++i) { const int ix = ib + (i & 3) + 8 * (i >> 2); const bool valid = ix >= 0 && ix <= 256; const float bb = tbl[valid ? ix : 0];
;                         sc[i] = valid ? sc[i] * (0.125f * LOG2E) + bb : NEGBIG; }
;                 } else {
; #pragma unroll
;                     for (int i = 0; i < 16; ++i) sc[i] = sc[i] * (0.125f * LOG2E) + tbl[ib + (i & 3) + 8 * (i >> 2)];
;                 }
;                 softmax2_pv(sc, m, l, o0, o1, vf);
.LBB0_120:
	s_add_i32 s18, s22, 64
	s_add_i32 s19, s35, s18
	s_cmp_ge_i32 s19, s3
	s_cselect_b64 s[24:25], -1, 0
	s_cmp_lt_i32 s19, s20
	s_cselect_b64 vcc, -1, 0
	s_and_b64 s[24:25], s[24:25], vcc
	s_andn2_b64 vcc, exec, s[24:25]
	s_cbranch_vccnz .LBB0_125
	v_or_b32_e32 v34, s18, v164
	v_mad_u32_u24 v118, v34, s26, v166
	ds_read_b128 v[34:37], v118
	ds_read_b128 v[114:117], v118 offset:32
	s_lshl_b32 s18, s18, 1
	s_waitcnt lgkmcnt(1)
	v_mfma_f32_32x32x16_bf16 v[34:49], v[34:37], v[110:113], 0
	s_waitcnt lgkmcnt(0)
	v_mfma_f32_32x32x16_bf16 v[34:49], v[114:117], v[106:109], v[34:49]
	ds_read_b128 v[114:117], v118 offset:64
	ds_read2_b32 v[162:163], v181 offset0:64 offset1:65
	ds_read2_b32 v[160:161], v181 offset0:66 offset1:67
	ds_read2_b32 v[154:155], v181 offset0:72 offset1:73
	ds_read2_b32 v[150:151], v181 offset0:74 offset1:75
	ds_read_b128 v[206:209], v118 offset:96
	ds_read2_b32 v[156:157], v181 offset0:80 offset1:81
	ds_read2_b32 v[158:159], v181 offset0:82 offset1:83
	ds_read2_b32 v[152:153], v181 offset0:88 offset1:89
	ds_read2_b32 v[148:149], v181 offset0:90 offset1:91
	s_waitcnt lgkmcnt(9)
	v_mfma_f32_32x32x16_bf16 v[34:49], v[114:117], v[102:105], v[34:49]
	v_add_u32_e32 v114, s18, v179
	v_add_u32_e32 v114, 0xd800, v114
	ds_read2_b64 v[118:121], v114 offset1:2
	ds_read2_b64 v[114:117], v114 offset0:4 offset1:6
	s_waitcnt lgkmcnt(6)
	v_mfma_f32_32x32x16_bf16 v[34:49], v[206:209], v[98:101], v[34:49]
	s_nop 11
	v_fmamk_f32 v199, v36, 0x3e38aa3b, v160
	v_fmamk_f32 v160, v40, 0x3e38aa3b, v150
	v_fmac_f32_e32 v151, 0x3e38aa3b, v41
	v_fmamk_f32 v200, v34, 0x3e38aa3b, v162
	v_fmac_f32_e32 v163, 0x3e38aa3b, v35
	v_fmac_f32_e32 v161, 0x3e38aa3b, v37
	v_fmamk_f32 v162, v38, 0x3e38aa3b, v154
	v_fmac_f32_e32 v155, 0x3e38aa3b, v39
	s_waitcnt lgkmcnt(5)
	v_fmac_f32_e32 v157, 0x3e38aa3b, v43
	s_waitcnt lgkmcnt(4)
	v_fmamk_f32 v150, v44, 0x3e38aa3b, v158
	v_fmac_f32_e32 v159, 0x3e38aa3b, v45
	s_waitcnt lgkmcnt(2)
	v_fmamk_f32 v43, v48, 0x3e38aa3b, v148
	v_fmac_f32_e32 v149, 0x3e38aa3b, v49
	v_max_f32_e32 v36, v160, v151
	v_fmamk_f32 v154, v42, 0x3e38aa3b, v156
	v_fmamk_f32 v44, v46, 0x3e38aa3b, v152
	v_fmac_f32_e32 v153, 0x3e38aa3b, v47
	v_max_f32_e32 v34, v200, v163
	v_max_f32_e32 v35, v199, v161
	v_max_f32_e32 v37, v150, v159
	v_max_f32_e32 v38, v43, v149
	v_max3_f32 v36, v162, v155, v36
	v_max3_f32 v37, v154, v157, v37
	v_max3_f32 v34, v34, v35, v36
	v_max3_f32 v35, v44, v153, v38
	v_max3_f32 v42, v34, v37, v35
	v_mov_b32_e32 v45, v42
	s_nop 1
	v_permlane32_swap_b32_e32 v45, v42
	v_add_u32_e32 v34, s18, v180
	v_add_u32_e32 v34, 0x6000, v34
	ds_read2_b64 v[38:41], v34 offset0:32 offset1:34
	ds_read2_b64 v[34:37], v34 offset0:36 offset1:38
	s_waitcnt lgkmcnt(2)
	v_max3_f32 v42, v198, v42, v45
	v_cmp_gt_f32_e32 vcc, v42, v198
	s_cbranch_vccz .LBB0_123
	v_sub_f32_e32 v45, v198, v42
	v_exp_f32_e32 v46, v45
	v_mov_b32_e32 v198, v42
	v_mul_f32_e32 v0, v0, v46
	v_pk_mul_f32 v[32:33], v[32:33], v[46:47] op_sel_hi:[1,0]
	v_pk_mul_f32 v[30:31], v[30:31], v[46:47] op_sel_hi:[1,0]
	v_pk_mul_f32 v[28:29], v[28:29], v[46:47] op_sel_hi:[1,0]
	v_pk_mul_f32 v[26:27], v[26:27], v[46:47] op_sel_hi:[1,0]
	v_pk_mul_f32 v[24:25], v[24:25], v[46:47] op_sel_hi:[1,0]
	v_pk_mul_f32 v[22:23], v[22:23], v[46:47] op_sel_hi:[1,0]
	v_pk_mul_f32 v[20:21], v[20:21], v[46:47] op_sel_hi:[1,0]
	v_pk_mul_f32 v[18:19], v[18:19], v[46:47] op_sel_hi:[1,0]
	v_pk_mul_f32 v[16:17], v[16:17], v[46:47] op_sel_hi:[1,0]
	v_pk_mul_f32 v[14:15], v[14:15], v[46:47] op_sel_hi:[1,0]
	v_pk_mul_f32 v[12:13], v[12:13], v[46:47] op_sel_hi:[1,0]
	v_pk_mul_f32 v[10:11], v[10:11], v[46:47] op_sel_hi:[1,0]
	v_pk_mul_f32 v[8:9], v[8:9], v[46:47] op_sel_hi:[1,0]
	v_pk_mul_f32 v[6:7], v[6:7], v[46:47] op_sel_hi:[1,0]
	v_pk_mul_f32 v[4:5], v[4:5], v[46:47] op_sel_hi:[1,0]
	v_pk_mul_f32 v[2:3], v[2:3], v[46:47] op_sel_hi:[1,0]
	s_branch .LBB0_124

; #define LAS __attribute__((address_space(3)))
; #define MFMA32(a, b, c) __builtin_amdgcn_mfma_f32_32x32x16_bf16((a), (b), (c), 0, 0, 0)
; __device__ __forceinline__ void gqa_phase(const PP P, LAS unsigned char* lds, int tid, int cb, int G) {
;     ...
;             for (int t = 0; t < 9; ++t) {
;                 const int kr0 = qoff + 32 * t, tok0 = m0 - 128 + kr0;
;                 if (tok0 < row0 || tok0 >= row0 + L) continue;
;                 bf16x8 kf[4];
; #pragma unroll
;                 for (int ds = 0; ds < 4; ++ds) kf[ds] = *(const LAS bf16x8*)(lds + GQ_K + (kr0 + r32) * GK_PITCH + (16 * ds + 8 * hi) * 2);
;                 bf16x8 vf[2][2];
; #pragma unroll
;                 for (int dh = 0; dh < 2; ++dh)
; #pragma unroll
;                     for (int s = 0; s < 2; ++s) { const LAS s16x4* vp = (const LAS s16x4*)(lds + GQ_V + (dh * 32 + r32) * GV_PITCH + (kr0 + 16 * s + 4 * hi) * 2);
;                         const s16x4 a = vp[0], c2 = vp[2]; vf[dh][s] = (bf16x8){a[0], a[1], a[2], a[3], c2[0], c2[1], c2[2], c2[3]}; }
;                 f32x16 sc = {};
; #pragma unroll
;                 for (int ds = 0; ds < 4; ++ds) sc = MFMA32(kf[ds], qr[ds], sc);
;                 const int ib = 32 * t - r32 + 4 * hi;
;                 if (t == 0 || t == 8) {
; #pragma unroll
;                     for (int i = 0; i < 16; ++i) { const int ix = ib + (i & 3) + 8 * (i >> 2); const bool valid = ix >= 0 && ix <= 256; const float bb = tbl[valid ? ix : 0];
;                         sc[i] = valid ? sc[i] * (0.125f * LOG2E) + bb : NEGBIG; }
;                 } else {
; #pragma unroll
;                     for (int i = 0; i < 16; ++i) sc[i] = sc[i] * (0.125f * LOG2E) + tbl[ib + (i & 3) + 8 * (i >> 2)];
;                 }
;                 softmax2_pv(sc, m, l, o0, o1, vf);
.LBB0_125:
	s_add_i32 s18, s22, 0x60
	s_add_i32 s19, s35, s18
	s_cmp_ge_i32 s19, s3
	s_cselect_b64 s[24:25], -1, 0
	s_cmp_lt_i32 s19, s20
	s_cselect_b64 vcc, -1, 0
	s_and_b64 s[24:25], s[24:25], vcc
	s_andn2_b64 vcc, exec, s[24:25]
	s_cbranch_vccnz .LBB0_130
	v_or_b32_e32 v34, s18, v164
	v_mad_u32_u24 v118, v34, s26, v166
	ds_read_b128 v[34:37], v118
	ds_read_b128 v[114:117], v118 offset:32
	s_lshl_b32 s18, s18, 1
	s_waitcnt lgkmcnt(1)
	v_mfma_f32_32x32x16_bf16 v[34:49], v[34:37], v[110:113], 0
	s_waitcnt lgkmcnt(0)
	v_mfma_f32_32x32x16_bf16 v[34:49], v[114:117], v[106:109], v[34:49]
	ds_read_b128 v[114:117], v118 offset:64
	ds_read2_b32 v[162:163], v181 offset0:96 offset1:97
	ds_read2_b32 v[160:161], v181 offset0:98 offset1:99
	ds_read2_b32 v[154:155], v181 offset0:104 offset1:105
	ds_read2_b32 v[150:151], v181 offset0:106 offset1:107
	ds_read_b128 v[206:209], v118 offset:96
	ds_read2_b32 v[156:157], v181 offset0:112 offset1:113
	ds_read2_b32 v[158:159], v181 offset0:114 offset1:115
	ds_read2_b32 v[152:153], v181 offset0:120 offset1:121
	ds_read2_b32 v[148:149], v181 offset0:122 offset1:123
	s_waitcnt lgkmcnt(9)
	v_mfma_f32_32x32x16_bf16 v[34:49], v[114:117], v[102:105], v[34:49]
	v_add_u32_e32 v114, s18, v179
	v_add_u32_e32 v114, 0xd800, v114
	ds_read2_b64 v[118:121], v114 offset1:2
	ds_read2_b64 v[114:117], v114 offset0:4 offset1:6
	s_waitcnt lgkmcnt(6)
	v_mfma_f32_32x32x16_bf16 v[34:49], v[206:209], v[98:101], v[34:49]
	s_nop 11
	v_fmamk_f32 v199, v36, 0x3e38aa3b, v160
	v_fmamk_f32 v160, v40, 0x3e38aa3b, v150
	v_fmac_f32_e32 v151, 0x3e38aa3b, v41
	v_fmamk_f32 v200, v34, 0x3e38aa3b, v162
	v_fmac_f32_e32 v163, 0x3e38aa3b, v35
	v_fmac_f32_e32 v161, 0x3e38aa3b, v37
	v_fmamk_f32 v162, v38, 0x3e38aa3b, v154
	v_fmac_f32_e32 v155, 0x3e38aa3b, v39
	s_waitcnt lgkmcnt(5)
	v_fmac_f32_e32 v157, 0x3e38aa3b, v43
	s_waitcnt lgkmcnt(4)
	v_fmamk_f32 v150, v44, 0x3e38aa3b, v158
	v_fmac_f32_e32 v159, 0x3e38aa3b, v45
	s_waitcnt lgkmcnt(2)
	v_fmamk_f32 v43, v48, 0x3e38aa3b, v148
	v_fmac_f32_e32 v149, 0x3e38aa3b, v49
	v_max_f32_e32 v36, v160, v151
	v_fmamk_f32 v154, v42, 0x3e38aa3b, v156
	v_fmamk_f32 v44, v46, 0x3e38aa3b, v152
	v_fmac_f32_e32 v153, 0x3e38aa3b, v47
	v_max_f32_e32 v34, v200, v163
	v_max_f32_e32 v35, v199, v161
	v_max_f32_e32 v37, v150, v159
	v_max_f32_e32 v38, v43, v149
	v_max3_f32 v36, v162, v155, v36
	v_max3_f32 v37, v154, v157, v37
	v_max3_f32 v34, v34, v35, v36
	v_max3_f32 v35, v44, v153, v38
	v_max3_f32 v42, v34, v37, v35
	v_mov_b32_e32 v45, v42
	s_nop 1
	v_permlane32_swap_b32_e32 v45, v42
	v_add_u32_e32 v34, s18, v180
	v_add_u32_e32 v34, 0x6000, v34
	ds_read2_b64 v[38:41], v34 offset0:32 offset1:34
	ds_read2_b64 v[34:37], v34 offset0:36 offset1:38
	s_waitcnt lgkmcnt(2)
	v_max3_f32 v42, v198, v42, v45
	v_cmp_gt_f32_e32 vcc, v42, v198
	s_cbranch_vccz .LBB0_128
	v_sub_f32_e32 v45, v198, v42
	v_exp_f32_e32 v46, v45
	v_mov_b32_e32 v198, v42
	v_mul_f32_e32 v0, v0, v46
	v_pk_mul_f32 v[32:33], v[32:33], v[46:47] op_sel_hi:[1,0]
	v_pk_mul_f32 v[30:31], v[30:31], v[46:47] op_sel_hi:[1,0]
	v_pk_mul_f32 v[28:29], v[28:29], v[46:47] op_sel_hi:[1,0]
	v_pk_mul_f32 v[26:27], v[26:27], v[46:47] op_sel_hi:[1,0]
	v_pk_mul_f32 v[24:25], v[24:25], v[46:47] op_sel_hi:[1,0]
	v_pk_mul_f32 v[22:23], v[22:23], v[46:47] op_sel_hi:[1,0]
	v_pk_mul_f32 v[20:21], v[20:21], v[46:47] op_sel_hi:[1,0]
	v_pk_mul_f32 v[18:19], v[18:19], v[46:47] op_sel_hi:[1,0]
	v_pk_mul_f32 v[16:17], v[16:17], v[46:47] op_sel_hi:[1,0]
	v_pk_mul_f32 v[14:15], v[14:15], v[46:47] op_sel_hi:[1,0]
	v_pk_mul_f32 v[12:13], v[12:13], v[46:47] op_sel_hi:[1,0]
	v_pk_mul_f32 v[10:11], v[10:11], v[46:47] op_sel_hi:[1,0]
	v_pk_mul_f32 v[8:9], v[8:9], v[46:47] op_sel_hi:[1,0]
	v_pk_mul_f32 v[6:7], v[6:7], v[46:47] op_sel_hi:[1,0]
	v_pk_mul_f32 v[4:5], v[4:5], v[46:47] op_sel_hi:[1,0]
	v_pk_mul_f32 v[2:3], v[2:3], v[46:47] op_sel_hi:[1,0]
	s_branch .LBB0_129

; #define LAS __attribute__((address_space(3)))
; #define MFMA32(a, b, c) __builtin_amdgcn_mfma_f32_32x32x16_bf16((a), (b), (c), 0, 0, 0)
; __device__ __forceinline__ void gqa_phase(const PP P, LAS unsigned char* lds, int tid, int cb, int G) {
;     ...
;             for (int t = 0; t < 9; ++t) {
;                 const int kr0 = qoff + 32 * t, tok0 = m0 - 128 + kr0;
;                 if (tok0 < row0 || tok0 >= row0 + L) continue;
;                 bf16x8 kf[4];
; #pragma unroll
;                 for (int ds = 0; ds < 4; ++ds) kf[ds] = *(const LAS bf16x8*)(lds + GQ_K + (kr0 + r32) * GK_PITCH + (16 * ds + 8 * hi) * 2);
;                 bf16x8 vf[2][2];
; #pragma unroll
;                 for (int dh = 0; dh < 2; ++dh)
; #pragma unroll
;                     for (int s = 0; s < 2; ++s) { const LAS s16x4* vp = (const LAS s16x4*)(lds + GQ_V + (dh * 32 + r32) * GV_PITCH + (kr0 + 16 * s + 4 * hi) * 2);
;                         const s16x4 a = vp[0], c2 = vp[2]; vf[dh][s] = (bf16x8){a[0], a[1], a[2], a[3], c2[0], c2[1], c2[2], c2[3]}; }
;                 f32x16 sc = {};
; #pragma unroll
;                 for (int ds = 0; ds < 4; ++ds) sc = MFMA32(kf[ds], qr[ds], sc);
;                 const int ib = 32 * t - r32 + 4 * hi;
;                 if (t == 0 || t == 8) {
; #pragma unroll
;                     for (int i = 0; i < 16; ++i) { const int ix = ib + (i & 3) + 8 * (i >> 2); const bool valid = ix >= 0 && ix <= 256; const float bb = tbl[valid ? ix : 0];
;                         sc[i] = valid ? sc[i] * (0.125f * LOG2E) + bb : NEGBIG; }
;                 } else {
; #pragma unroll
;                     for (int i = 0; i < 16; ++i) sc[i] = sc[i] * (0.125f * LOG2E) + tbl[ib + (i & 3) + 8 * (i >> 2)];
;                 }
;                 softmax2_pv(sc, m, l, o0, o1, vf);
.LBB0_130:
	s_or_b32 s18, s22, 0x80
	s_add_i32 s19, s35, s18
	s_cmp_ge_i32 s19, s3
	s_cselect_b64 s[24:25], -1, 0
	s_cmp_lt_i32 s19, s20
	s_cselect_b64 vcc, -1, 0
	s_and_b64 s[24:25], s[24:25], vcc
	s_andn2_b64 vcc, exec, s[24:25]
	s_cbranch_vccnz .LBB0_135
	v_or_b32_e32 v34, s18, v164
	v_mad_u32_u24 v118, v34, s26, v166
	ds_read_b128 v[34:37], v118
	ds_read_b128 v[114:117], v118 offset:32
	s_lshl_b32 s18, s18, 1
	s_waitcnt lgkmcnt(1)
	v_mfma_f32_32x32x16_bf16 v[34:49], v[34:37], v[110:113], 0
	s_waitcnt lgkmcnt(0)
	v_mfma_f32_32x32x16_bf16 v[34:49], v[114:117], v[106:109], v[34:49]
	ds_read_b128 v[114:117], v118 offset:64
	ds_read2_b32 v[162:163], v181 offset0:128 offset1:129
	ds_read2_b32 v[160:161], v181 offset0:130 offset1:131
	ds_read2_b32 v[154:155], v181 offset0:136 offset1:137
	ds_read2_b32 v[150:151], v181 offset0:138 offset1:139
	ds_read_b128 v[206:209], v118 offset:96
	ds_read2_b32 v[156:157], v181 offset0:144 offset1:145
	ds_read2_b32 v[158:159], v181 offset0:146 offset1:147
	ds_read2_b32 v[152:153], v181 offset0:152 offset1:153
	ds_read2_b32 v[148:149], v181 offset0:154 offset1:155
	s_waitcnt lgkmcnt(9)
	v_mfma_f32_32x32x16_bf16 v[34:49], v[114:117], v[102:105], v[34:49]
	v_add_u32_e32 v114, s18, v179
	v_add_u32_e32 v114, 0xd800, v114
	ds_read2_b64 v[118:121], v114 offset1:2
	ds_read2_b64 v[114:117], v114 offset0:4 offset1:6
	s_waitcnt lgkmcnt(6)
	v_mfma_f32_32x32x16_bf16 v[34:49], v[206:209], v[98:101], v[34:49]
	s_nop 11
	v_fmamk_f32 v199, v36, 0x3e38aa3b, v160
	v_fmamk_f32 v160, v40, 0x3e38aa3b, v150
	v_fmac_f32_e32 v151, 0x3e38aa3b, v41
	v_fmamk_f32 v200, v34, 0x3e38aa3b, v162
	v_fmac_f32_e32 v163, 0x3e38aa3b, v35
	v_fmac_f32_e32 v161, 0x3e38aa3b, v37
	v_fmamk_f32 v162, v38, 0x3e38aa3b, v154
	v_fmac_f32_e32 v155, 0x3e38aa3b, v39
	s_waitcnt lgkmcnt(5)
	v_fmac_f32_e32 v157, 0x3e38aa3b, v43
	s_waitcnt lgkmcnt(4)
	v_fmamk_f32 v150, v44, 0x3e38aa3b, v158
	v_fmac_f32_e32 v159, 0x3e38aa3b, v45
	s_waitcnt lgkmcnt(2)
	v_fmamk_f32 v43, v48, 0x3e38aa3b, v148
	v_fmac_f32_e32 v149, 0x3e38aa3b, v49
	v_max_f32_e32 v36, v160, v151
	v_fmamk_f32 v154, v42, 0x3e38aa3b, v156
	v_fmamk_f32 v44, v46, 0x3e38aa3b, v152
	v_fmac_f32_e32 v153, 0x3e38aa3b, v47
	v_max_f32_e32 v34, v200, v163
	v_max_f32_e32 v35, v199, v161
	v_max_f32_e32 v37, v150, v159
	v_max_f32_e32 v38, v43, v149
	v_max3_f32 v36, v162, v155, v36
	v_max3_f32 v37, v154, v157, v37
	v_max3_f32 v34, v34, v35, v36
	v_max3_f32 v35, v44, v153, v38
	v_max3_f32 v42, v34, v37, v35
	v_mov_b32_e32 v45, v42
	s_nop 1
	v_permlane32_swap_b32_e32 v45, v42
	v_add_u32_e32 v34, s18, v180
	v_add_u32_e32 v34, 0x6000, v34
	ds_read2_b64 v[38:41], v34 offset0:32 offset1:34
	ds_read2_b64 v[34:37], v34 offset0:36 offset1:38
	s_waitcnt lgkmcnt(2)
	v_max3_f32 v42, v198, v42, v45
	v_cmp_gt_f32_e32 vcc, v42, v198
	s_cbranch_vccz .LBB0_133
	v_sub_f32_e32 v45, v198, v42
	v_exp_f32_e32 v46, v45
	v_mov_b32_e32 v198, v42
	v_mul_f32_e32 v0, v0, v46
	v_pk_mul_f32 v[32:33], v[32:33], v[46:47] op_sel_hi:[1,0]
	v_pk_mul_f32 v[30:31], v[30:31], v[46:47] op_sel_hi:[1,0]
	v_pk_mul_f32 v[28:29], v[28:29], v[46:47] op_sel_hi:[1,0]
	v_pk_mul_f32 v[26:27], v[26:27], v[46:47] op_sel_hi:[1,0]
	v_pk_mul_f32 v[24:25], v[24:25], v[46:47] op_sel_hi:[1,0]
	v_pk_mul_f32 v[22:23], v[22:23], v[46:47] op_sel_hi:[1,0]
	v_pk_mul_f32 v[20:21], v[20:21], v[46:47] op_sel_hi:[1,0]
	v_pk_mul_f32 v[18:19], v[18:19], v[46:47] op_sel_hi:[1,0]
	v_pk_mul_f32 v[16:17], v[16:17], v[46:47] op_sel_hi:[1,0]
	v_pk_mul_f32 v[14:15], v[14:15], v[46:47] op_sel_hi:[1,0]
	v_pk_mul_f32 v[12:13], v[12:13], v[46:47] op_sel_hi:[1,0]
	v_pk_mul_f32 v[10:11], v[10:11], v[46:47] op_sel_hi:[1,0]
	v_pk_mul_f32 v[8:9], v[8:9], v[46:47] op_sel_hi:[1,0]
	v_pk_mul_f32 v[6:7], v[6:7], v[46:47] op_sel_hi:[1,0]
	v_pk_mul_f32 v[4:5], v[4:5], v[46:47] op_sel_hi:[1,0]
	v_pk_mul_f32 v[2:3], v[2:3], v[46:47] op_sel_hi:[1,0]
	s_branch .LBB0_134

; #define LAS __attribute__((address_space(3)))
; #define MFMA32(a, b, c) __builtin_amdgcn_mfma_f32_32x32x16_bf16((a), (b), (c), 0, 0, 0)
; __device__ __forceinline__ void gqa_phase(const PP P, LAS unsigned char* lds, int tid, int cb, int G) {
;     ...
;             for (int t = 0; t < 9; ++t) {
;                 const int kr0 = qoff + 32 * t, tok0 = m0 - 128 + kr0;
;                 if (tok0 < row0 || tok0 >= row0 + L) continue;
;                 bf16x8 kf[4];
; #pragma unroll
;                 for (int ds = 0; ds < 4; ++ds) kf[ds] = *(const LAS bf16x8*)(lds + GQ_K + (kr0 + r32) * GK_PITCH + (16 * ds + 8 * hi) * 2);
;                 bf16x8 vf[2][2];
; #pragma unroll
;                 for (int dh = 0; dh < 2; ++dh)
; #pragma unroll
;                     for (int s = 0; s < 2; ++s) { const LAS s16x4* vp = (const LAS s16x4*)(lds + GQ_V + (dh * 32 + r32) * GV_PITCH + (kr0 + 16 * s + 4 * hi) * 2);
;                         const s16x4 a = vp[0], c2 = vp[2]; vf[dh][s] = (bf16x8){a[0], a[1], a[2], a[3], c2[0], c2[1], c2[2], c2[3]}; }
;                 f32x16 sc = {};
; #pragma unroll
;                 for (int ds = 0; ds < 4; ++ds) sc = MFMA32(kf[ds], qr[ds], sc);
;                 const int ib = 32 * t - r32 + 4 * hi;
;                 if (t == 0 || t == 8) {
; #pragma unroll
;                     for (int i = 0; i < 16; ++i) { const int ix = ib + (i & 3) + 8 * (i >> 2); const bool valid = ix >= 0 && ix <= 256; const float bb = tbl[valid ? ix : 0];
;                         sc[i] = valid ? sc[i] * (0.125f * LOG2E) + bb : NEGBIG; }
;                 } else {
; #pragma unroll
;                     for (int i = 0; i < 16; ++i) sc[i] = sc[i] * (0.125f * LOG2E) + tbl[ib + (i & 3) + 8 * (i >> 2)];
;                 }
;                 softmax2_pv(sc, m, l, o0, o1, vf);
.LBB0_135:
	s_add_i32 s18, s22, 0xa0
	s_add_i32 s19, s35, s18
	s_cmp_ge_i32 s19, s3
	s_cselect_b64 s[24:25], -1, 0
	s_cmp_lt_i32 s19, s20
	s_cselect_b64 vcc, -1, 0
	s_and_b64 s[24:25], s[24:25], vcc
	s_andn2_b64 vcc, exec, s[24:25]
	s_cbranch_vccnz .LBB0_140
	v_or_b32_e32 v34, s18, v164
	v_mad_u32_u24 v118, v34, s26, v166
	ds_read_b128 v[34:37], v118
	ds_read_b128 v[114:117], v118 offset:32
	s_lshl_b32 s18, s18, 1
	s_waitcnt lgkmcnt(1)
	v_mfma_f32_32x32x16_bf16 v[34:49], v[34:37], v[110:113], 0
	s_waitcnt lgkmcnt(0)
	v_mfma_f32_32x32x16_bf16 v[34:49], v[114:117], v[106:109], v[34:49]
	ds_read_b128 v[114:117], v118 offset:64
	ds_read2_b32 v[162:163], v181 offset0:160 offset1:161
	ds_read2_b32 v[160:161], v181 offset0:162 offset1:163
	ds_read2_b32 v[154:155], v181 offset0:168 offset1:169
	ds_read2_b32 v[150:151], v181 offset0:170 offset1:171
	ds_read_b128 v[206:209], v118 offset:96
	ds_read2_b32 v[156:157], v181 offset0:176 offset1:177
	ds_read2_b32 v[158:159], v181 offset0:178 offset1:179
	ds_read2_b32 v[152:153], v181 offset0:184 offset1:185
	ds_read2_b32 v[148:149], v181 offset0:186 offset1:187
	s_waitcnt lgkmcnt(9)
	v_mfma_f32_32x32x16_bf16 v[34:49], v[114:117], v[102:105], v[34:49]
	v_add_u32_e32 v114, s18, v179
	v_add_u32_e32 v114, 0xd800, v114
	ds_read2_b64 v[118:121], v114 offset1:2
	ds_read2_b64 v[114:117], v114 offset0:4 offset1:6
	s_waitcnt lgkmcnt(6)
	v_mfma_f32_32x32x16_bf16 v[34:49], v[206:209], v[98:101], v[34:49]
	s_nop 11
	v_fmamk_f32 v199, v36, 0x3e38aa3b, v160
	v_fmamk_f32 v160, v40, 0x3e38aa3b, v150
	v_fmac_f32_e32 v151, 0x3e38aa3b, v41
	v_fmamk_f32 v200, v34, 0x3e38aa3b, v162
	v_fmac_f32_e32 v163, 0x3e38aa3b, v35
	v_fmac_f32_e32 v161, 0x3e38aa3b, v37
	v_fmamk_f32 v162, v38, 0x3e38aa3b, v154
	v_fmac_f32_e32 v155, 0x3e38aa3b, v39
	s_waitcnt lgkmcnt(5)
	v_fmac_f32_e32 v157, 0x3e38aa3b, v43
	s_waitcnt lgkmcnt(4)
	v_fmamk_f32 v150, v44, 0x3e38aa3b, v158
	v_fmac_f32_e32 v159, 0x3e38aa3b, v45
	s_waitcnt lgkmcnt(2)
	v_fmamk_f32 v43, v48, 0x3e38aa3b, v148
	v_fmac_f32_e32 v149, 0x3e38aa3b, v49
	v_max_f32_e32 v36, v160, v151
	v_fmamk_f32 v154, v42, 0x3e38aa3b, v156
	v_fmamk_f32 v44, v46, 0x3e38aa3b, v152
	v_fmac_f32_e32 v153, 0x3e38aa3b, v47
	v_max_f32_e32 v34, v200, v163
	v_max_f32_e32 v35, v199, v161
	v_max_f32_e32 v37, v150, v159
	v_max_f32_e32 v38, v43, v149
	v_max3_f32 v36, v162, v155, v36
	v_max3_f32 v37, v154, v157, v37
	v_max3_f32 v34, v34, v35, v36
	v_max3_f32 v35, v44, v153, v38
	v_max3_f32 v42, v34, v37, v35
	v_mov_b32_e32 v45, v42
	s_nop 1
	v_permlane32_swap_b32_e32 v45, v42
	v_add_u32_e32 v34, s18, v180
	v_add_u32_e32 v34, 0x6000, v34
	ds_read2_b64 v[38:41], v34 offset0:32 offset1:34
	ds_read2_b64 v[34:37], v34 offset0:36 offset1:38
	s_waitcnt lgkmcnt(2)
	v_max3_f32 v42, v198, v42, v45
	v_cmp_gt_f32_e32 vcc, v42, v198
	s_cbranch_vccz .LBB0_138
	v_sub_f32_e32 v45, v198, v42
	v_exp_f32_e32 v46, v45
	v_mov_b32_e32 v198, v42
	v_mul_f32_e32 v0, v0, v46
	v_pk_mul_f32 v[32:33], v[32:33], v[46:47] op_sel_hi:[1,0]
	v_pk_mul_f32 v[30:31], v[30:31], v[46:47] op_sel_hi:[1,0]
	v_pk_mul_f32 v[28:29], v[28:29], v[46:47] op_sel_hi:[1,0]
	v_pk_mul_f32 v[26:27], v[26:27], v[46:47] op_sel_hi:[1,0]
	v_pk_mul_f32 v[24:25], v[24:25], v[46:47] op_sel_hi:[1,0]
	v_pk_mul_f32 v[22:23], v[22:23], v[46:47] op_sel_hi:[1,0]
	v_pk_mul_f32 v[20:21], v[20:21], v[46:47] op_sel_hi:[1,0]
	v_pk_mul_f32 v[18:19], v[18:19], v[46:47] op_sel_hi:[1,0]
	v_pk_mul_f32 v[16:17], v[16:17], v[46:47] op_sel_hi:[1,0]
	v_pk_mul_f32 v[14:15], v[14:15], v[46:47] op_sel_hi:[1,0]
	v_pk_mul_f32 v[12:13], v[12:13], v[46:47] op_sel_hi:[1,0]
	v_pk_mul_f32 v[10:11], v[10:11], v[46:47] op_sel_hi:[1,0]
	v_pk_mul_f32 v[8:9], v[8:9], v[46:47] op_sel_hi:[1,0]
	v_pk_mul_f32 v[6:7], v[6:7], v[46:47] op_sel_hi:[1,0]
	v_pk_mul_f32 v[4:5], v[4:5], v[46:47] op_sel_hi:[1,0]
	v_pk_mul_f32 v[2:3], v[2:3], v[46:47] op_sel_hi:[1,0]
	s_branch .LBB0_139

; #define LAS __attribute__((address_space(3)))
; #define MFMA32(a, b, c) __builtin_amdgcn_mfma_f32_32x32x16_bf16((a), (b), (c), 0, 0, 0)
; __device__ __forceinline__ void gqa_phase(const PP P, LAS unsigned char* lds, int tid, int cb, int G) {
;     ...
;             for (int t = 0; t < 9; ++t) {
;                 const int kr0 = qoff + 32 * t, tok0 = m0 - 128 + kr0;
;                 if (tok0 < row0 || tok0 >= row0 + L) continue;
;                 bf16x8 kf[4];
; #pragma unroll
;                 for (int ds = 0; ds < 4; ++ds) kf[ds] = *(const LAS bf16x8*)(lds + GQ_K + (kr0 + r32) * GK_PITCH + (16 * ds + 8 * hi) * 2);
;                 bf16x8 vf[2][2];
; #pragma unroll
;                 for (int dh = 0; dh < 2; ++dh)
; #pragma unroll
;                     for (int s = 0; s < 2; ++s) { const LAS s16x4* vp = (const LAS s16x4*)(lds + GQ_V + (dh * 32 + r32) * GV_PITCH + (kr0 + 16 * s + 4 * hi) * 2);
;                         const s16x4 a = vp[0], c2 = vp[2]; vf[dh][s] = (bf16x8){a[0], a[1], a[2], a[3], c2[0], c2[1], c2[2], c2[3]}; }
;                 f32x16 sc = {};
; #pragma unroll
;                 for (int ds = 0; ds < 4; ++ds) sc = MFMA32(kf[ds], qr[ds], sc);
;                 const int ib = 32 * t - r32 + 4 * hi;
;                 if (t == 0 || t == 8) {
; #pragma unroll
;                     for (int i = 0; i < 16; ++i) { const int ix = ib + (i & 3) + 8 * (i >> 2); const bool valid = ix >= 0 && ix <= 256; const float bb = tbl[valid ? ix : 0];
;                         sc[i] = valid ? sc[i] * (0.125f * LOG2E) + bb : NEGBIG; }
;                 } else {
; #pragma unroll
;                     for (int i = 0; i < 16; ++i) sc[i] = sc[i] * (0.125f * LOG2E) + tbl[ib + (i & 3) + 8 * (i >> 2)];
;                 }
;                 softmax2_pv(sc, m, l, o0, o1, vf);
.LBB0_140:
	s_add_i32 s18, s22, 0xc0
	s_add_i32 s19, s35, s18
	s_cmp_ge_i32 s19, s3
	s_cselect_b64 s[24:25], -1, 0
	s_cmp_lt_i32 s19, s20
	s_cselect_b64 vcc, -1, 0
	s_and_b64 s[24:25], s[24:25], vcc
	s_andn2_b64 vcc, exec, s[24:25]
	s_cbranch_vccnz .LBB0_145
	v_or_b32_e32 v34, s18, v164
	v_mad_u32_u24 v118, v34, s26, v166
	ds_read_b128 v[34:37], v118
	ds_read_b128 v[114:117], v118 offset:32
	s_lshl_b32 s18, s18, 1
	s_waitcnt lgkmcnt(1)
	v_mfma_f32_32x32x16_bf16 v[34:49], v[34:37], v[110:113], 0
	s_waitcnt lgkmcnt(0)
	v_mfma_f32_32x32x16_bf16 v[34:49], v[114:117], v[106:109], v[34:49]
	ds_read_b128 v[114:117], v118 offset:64
	ds_read2_b32 v[162:163], v181 offset0:192 offset1:193
	ds_read2_b32 v[160:161], v181 offset0:194 offset1:195
	ds_read2_b32 v[154:155], v181 offset0:200 offset1:201
	ds_read2_b32 v[150:151], v181 offset0:202 offset1:203
	ds_read_b128 v[206:209], v118 offset:96
	ds_read2_b32 v[156:157], v181 offset0:208 offset1:209
	ds_read2_b32 v[158:159], v181 offset0:210 offset1:211
	ds_read2_b32 v[152:153], v181 offset0:216 offset1:217
	ds_read2_b32 v[148:149], v181 offset0:218 offset1:219
	s_waitcnt lgkmcnt(9)
	v_mfma_f32_32x32x16_bf16 v[34:49], v[114:117], v[102:105], v[34:49]
	v_add_u32_e32 v114, s18, v179
	v_add_u32_e32 v114, 0xd800, v114
	ds_read2_b64 v[118:121], v114 offset1:2
	ds_read2_b64 v[114:117], v114 offset0:4 offset1:6
	s_waitcnt lgkmcnt(6)
	v_mfma_f32_32x32x16_bf16 v[34:49], v[206:209], v[98:101], v[34:49]
	s_nop 11
	v_fmamk_f32 v199, v36, 0x3e38aa3b, v160
	v_fmamk_f32 v160, v40, 0x3e38aa3b, v150
	v_fmac_f32_e32 v151, 0x3e38aa3b, v41
	v_fmamk_f32 v200, v34, 0x3e38aa3b, v162
	v_fmac_f32_e32 v163, 0x3e38aa3b, v35
	v_fmac_f32_e32 v161, 0x3e38aa3b, v37
	v_fmamk_f32 v162, v38, 0x3e38aa3b, v154
	v_fmac_f32_e32 v155, 0x3e38aa3b, v39
	s_waitcnt lgkmcnt(5)
	v_fmac_f32_e32 v157, 0x3e38aa3b, v43
	s_waitcnt lgkmcnt(4)
	v_fmamk_f32 v150, v44, 0x3e38aa3b, v158
	v_fmac_f32_e32 v159, 0x3e38aa3b, v45
	s_waitcnt lgkmcnt(2)
	v_fmamk_f32 v43, v48, 0x3e38aa3b, v148
	v_fmac_f32_e32 v149, 0x3e38aa3b, v49
	v_max_f32_e32 v36, v160, v151
	v_fmamk_f32 v154, v42, 0x3e38aa3b, v156
	v_fmamk_f32 v44, v46, 0x3e38aa3b, v152
	v_fmac_f32_e32 v153, 0x3e38aa3b, v47
	v_max_f32_e32 v34, v200, v163
	v_max_f32_e32 v35, v199, v161
	v_max_f32_e32 v37, v150, v159
	v_max_f32_e32 v38, v43, v149
	v_max3_f32 v36, v162, v155, v36
	v_max3_f32 v37, v154, v157, v37
	v_max3_f32 v34, v34, v35, v36
	v_max3_f32 v35, v44, v153, v38
	v_max3_f32 v42, v34, v37, v35
	v_mov_b32_e32 v45, v42
	s_nop 1
	v_permlane32_swap_b32_e32 v45, v42
	v_add_u32_e32 v34, s18, v180
	v_add_u32_e32 v34, 0x6000, v34
	ds_read2_b64 v[38:41], v34 offset0:32 offset1:34
	ds_read2_b64 v[34:37], v34 offset0:36 offset1:38
	s_waitcnt lgkmcnt(2)
	v_max3_f32 v42, v198, v42, v45
	v_cmp_gt_f32_e32 vcc, v42, v198
	s_cbranch_vccz .LBB0_143
	v_sub_f32_e32 v45, v198, v42
	v_exp_f32_e32 v46, v45
	v_mov_b32_e32 v198, v42
	v_mul_f32_e32 v0, v0, v46
	v_pk_mul_f32 v[32:33], v[32:33], v[46:47] op_sel_hi:[1,0]
	v_pk_mul_f32 v[30:31], v[30:31], v[46:47] op_sel_hi:[1,0]
	v_pk_mul_f32 v[28:29], v[28:29], v[46:47] op_sel_hi:[1,0]
	v_pk_mul_f32 v[26:27], v[26:27], v[46:47] op_sel_hi:[1,0]
	v_pk_mul_f32 v[24:25], v[24:25], v[46:47] op_sel_hi:[1,0]
	v_pk_mul_f32 v[22:23], v[22:23], v[46:47] op_sel_hi:[1,0]
	v_pk_mul_f32 v[20:21], v[20:21], v[46:47] op_sel_hi:[1,0]
	v_pk_mul_f32 v[18:19], v[18:19], v[46:47] op_sel_hi:[1,0]
	v_pk_mul_f32 v[16:17], v[16:17], v[46:47] op_sel_hi:[1,0]
	v_pk_mul_f32 v[14:15], v[14:15], v[46:47] op_sel_hi:[1,0]
	v_pk_mul_f32 v[12:13], v[12:13], v[46:47] op_sel_hi:[1,0]
	v_pk_mul_f32 v[10:11], v[10:11], v[46:47] op_sel_hi:[1,0]
	v_pk_mul_f32 v[8:9], v[8:9], v[46:47] op_sel_hi:[1,0]
	v_pk_mul_f32 v[6:7], v[6:7], v[46:47] op_sel_hi:[1,0]
	v_pk_mul_f32 v[4:5], v[4:5], v[46:47] op_sel_hi:[1,0]
	v_pk_mul_f32 v[2:3], v[2:3], v[46:47] op_sel_hi:[1,0]
	s_branch .LBB0_144

; #define LAS __attribute__((address_space(3)))
; #define MFMA32(a, b, c) __builtin_amdgcn_mfma_f32_32x32x16_bf16((a), (b), (c), 0, 0, 0)
; __device__ __forceinline__ void gqa_phase(const PP P, LAS unsigned char* lds, int tid, int cb, int G) {
;     ...
;             for (int t = 0; t < 9; ++t) {
;                 const int kr0 = qoff + 32 * t, tok0 = m0 - 128 + kr0;
;                 if (tok0 < row0 || tok0 >= row0 + L) continue;
;                 bf16x8 kf[4];
; #pragma unroll
;                 for (int ds = 0; ds < 4; ++ds) kf[ds] = *(const LAS bf16x8*)(lds + GQ_K + (kr0 + r32) * GK_PITCH + (16 * ds + 8 * hi) * 2);
;                 bf16x8 vf[2][2];
; #pragma unroll
;                 for (int dh = 0; dh < 2; ++dh)
; #pragma unroll
;                     for (int s = 0; s < 2; ++s) { const LAS s16x4* vp = (const LAS s16x4*)(lds + GQ_V + (dh * 32 + r32) * GV_PITCH + (kr0 + 16 * s + 4 * hi) * 2);
;                         const s16x4 a = vp[0], c2 = vp[2]; vf[dh][s] = (bf16x8){a[0], a[1], a[2], a[3], c2[0], c2[1], c2[2], c2[3]}; }
;                 f32x16 sc = {};
; #pragma unroll
;                 for (int ds = 0; ds < 4; ++ds) sc = MFMA32(kf[ds], qr[ds], sc);
;                 const int ib = 32 * t - r32 + 4 * hi;
;                 if (t == 0 || t == 8) {
; #pragma unroll
;                     for (int i = 0; i < 16; ++i) { const int ix = ib + (i & 3) + 8 * (i >> 2); const bool valid = ix >= 0 && ix <= 256; const float bb = tbl[valid ? ix : 0];
;                         sc[i] = valid ? sc[i] * (0.125f * LOG2E) + bb : NEGBIG; }
;                 } else {
; #pragma unroll
;                     for (int i = 0; i < 16; ++i) sc[i] = sc[i] * (0.125f * LOG2E) + tbl[ib + (i & 3) + 8 * (i >> 2)];
;                 }
;                 softmax2_pv(sc, m, l, o0, o1, vf);
.LBB0_145:
	s_add_i32 s18, s22, 0xe0
	s_add_i32 s19, s35, s18
	s_cmp_ge_i32 s19, s3
	s_cselect_b64 s[24:25], -1, 0
	s_cmp_lt_i32 s19, s20
	s_cselect_b64 vcc, -1, 0
	s_and_b64 s[24:25], s[24:25], vcc
	s_andn2_b64 vcc, exec, s[24:25]
	s_cbranch_vccnz .LBB0_150
	v_or_b32_e32 v34, s18, v164
	v_mad_u32_u24 v118, v34, s26, v166
	ds_read_b128 v[34:37], v118
	ds_read_b128 v[114:117], v118 offset:32
	s_lshl_b32 s18, s18, 1
	s_waitcnt lgkmcnt(1)
	v_mfma_f32_32x32x16_bf16 v[34:49], v[34:37], v[110:113], 0
	s_waitcnt lgkmcnt(0)
	v_mfma_f32_32x32x16_bf16 v[34:49], v[114:117], v[106:109], v[34:49]
	ds_read_b128 v[114:117], v118 offset:64
	ds_read2_b32 v[162:163], v181 offset0:224 offset1:225
	ds_read2_b32 v[160:161], v181 offset0:226 offset1:227
	ds_read2_b32 v[154:155], v181 offset0:232 offset1:233
	ds_read2_b32 v[150:151], v181 offset0:234 offset1:235
	ds_read_b128 v[206:209], v118 offset:96
	ds_read2_b32 v[156:157], v181 offset0:240 offset1:241
	ds_read2_b32 v[158:159], v181 offset0:242 offset1:243
	ds_read2_b32 v[152:153], v181 offset0:248 offset1:249
	ds_read2_b32 v[148:149], v181 offset0:250 offset1:251
	s_waitcnt lgkmcnt(9)
	v_mfma_f32_32x32x16_bf16 v[34:49], v[114:117], v[102:105], v[34:49]
	v_add_u32_e32 v114, s18, v179
	v_add_u32_e32 v114, 0xd800, v114
	ds_read2_b64 v[118:121], v114 offset1:2
	ds_read2_b64 v[114:117], v114 offset0:4 offset1:6
	s_waitcnt lgkmcnt(6)
	v_mfma_f32_32x32x16_bf16 v[34:49], v[206:209], v[98:101], v[34:49]
	s_nop 11
	v_fmamk_f32 v199, v36, 0x3e38aa3b, v160
	v_fmamk_f32 v160, v40, 0x3e38aa3b, v150
	v_fmac_f32_e32 v151, 0x3e38aa3b, v41
	v_fmamk_f32 v200, v34, 0x3e38aa3b, v162
	v_fmac_f32_e32 v163, 0x3e38aa3b, v35
	v_fmac_f32_e32 v161, 0x3e38aa3b, v37
	v_fmamk_f32 v162, v38, 0x3e38aa3b, v154
	v_fmac_f32_e32 v155, 0x3e38aa3b, v39
	s_waitcnt lgkmcnt(5)
	v_fmac_f32_e32 v157, 0x3e38aa3b, v43
	s_waitcnt lgkmcnt(4)
	v_fmamk_f32 v150, v44, 0x3e38aa3b, v158
	v_fmac_f32_e32 v159, 0x3e38aa3b, v45
	s_waitcnt lgkmcnt(2)
	v_fmamk_f32 v43, v48, 0x3e38aa3b, v148
	v_fmac_f32_e32 v149, 0x3e38aa3b, v49
	v_max_f32_e32 v36, v160, v151
	v_fmamk_f32 v154, v42, 0x3e38aa3b, v156
	v_fmamk_f32 v44, v46, 0x3e38aa3b, v152
	v_fmac_f32_e32 v153, 0x3e38aa3b, v47
	v_max_f32_e32 v34, v200, v163
	v_max_f32_e32 v35, v199, v161
	v_max_f32_e32 v37, v150, v159
	v_max_f32_e32 v38, v43, v149
	v_max3_f32 v36, v162, v155, v36
	v_max3_f32 v37, v154, v157, v37
	v_max3_f32 v34, v34, v35, v36
	v_max3_f32 v35, v44, v153, v38
	v_max3_f32 v42, v34, v37, v35
	v_mov_b32_e32 v45, v42
	s_nop 1
	v_permlane32_swap_b32_e32 v45, v42
	v_add_u32_e32 v34, s18, v180
	v_add_u32_e32 v34, 0x6000, v34
	ds_read2_b64 v[38:41], v34 offset0:32 offset1:34
	ds_read2_b64 v[34:37], v34 offset0:36 offset1:38
	s_waitcnt lgkmcnt(2)
	v_max3_f32 v42, v198, v42, v45
	v_cmp_gt_f32_e32 vcc, v42, v198
	s_cbranch_vccz .LBB0_148
	v_sub_f32_e32 v45, v198, v42
	v_exp_f32_e32 v46, v45
	v_mov_b32_e32 v198, v42
	v_mul_f32_e32 v0, v0, v46
	v_pk_mul_f32 v[32:33], v[32:33], v[46:47] op_sel_hi:[1,0]
	v_pk_mul_f32 v[30:31], v[30:31], v[46:47] op_sel_hi:[1,0]
	v_pk_mul_f32 v[28:29], v[28:29], v[46:47] op_sel_hi:[1,0]
	v_pk_mul_f32 v[26:27], v[26:27], v[46:47] op_sel_hi:[1,0]
	v_pk_mul_f32 v[24:25], v[24:25], v[46:47] op_sel_hi:[1,0]
	v_pk_mul_f32 v[22:23], v[22:23], v[46:47] op_sel_hi:[1,0]
	v_pk_mul_f32 v[20:21], v[20:21], v[46:47] op_sel_hi:[1,0]
	v_pk_mul_f32 v[18:19], v[18:19], v[46:47] op_sel_hi:[1,0]
	v_pk_mul_f32 v[16:17], v[16:17], v[46:47] op_sel_hi:[1,0]
	v_pk_mul_f32 v[14:15], v[14:15], v[46:47] op_sel_hi:[1,0]
	v_pk_mul_f32 v[12:13], v[12:13], v[46:47] op_sel_hi:[1,0]
	v_pk_mul_f32 v[10:11], v[10:11], v[46:47] op_sel_hi:[1,0]
	v_pk_mul_f32 v[8:9], v[8:9], v[46:47] op_sel_hi:[1,0]
	v_pk_mul_f32 v[6:7], v[6:7], v[46:47] op_sel_hi:[1,0]
	v_pk_mul_f32 v[4:5], v[4:5], v[46:47] op_sel_hi:[1,0]
	v_pk_mul_f32 v[2:3], v[2:3], v[46:47] op_sel_hi:[1,0]
	s_branch .LBB0_149
